# work-queue pop: the atomic's return lands directly in the next-item register and is waited for only where it is published at the end of the unit (P2 and P4), instead of right after issue
# baseline (speedup 1.0000x reference)
; #define PG8_LAS __attribute__((address_space(3)))
; __device__ __forceinline__ int wg_tid(PG8_LAS unsigned char* ldsbase) {
;     const unsigned hw = (unsigned)__builtin_amdgcn_s_getreg((5 << 11) | 4) & 63u;
;     const unsigned wv = ((volatile PG8_LAS unsigned*)(ldsbase + WMAP_OFF))[hw];
;     const int lane = (int)__builtin_amdgcn_mbcnt_hi(~0u, __builtin_amdgcn_mbcnt_lo(~0u, 0u));
;     int t = (int)__builtin_amdgcn_readfirstlane(wv) * 64 + lane;
;     asm volatile("" : "+v"(t));
;     return t;
; __global__ void __launch_bounds__(512, 2) fwd_megakernel(Ptrs Parg) {
;     ...
;           while (it < 28 * NCH) { const int t2 = pg8::wg_tid(glds);
;               if (t2 == 0) nxt = atomicAdd(qctr, 1u);
.LBB0_299:
	s_movk_i32 s100, 0xc18
	s_movk_i32 s101, 0xfdfc
	s_cmp_lt_u32 s74, 0x204
	s_cselect_b32 s100, s100, s101
	s_add_i32 s74, s74, s100
	s_getreg_b32 s3, hwreg(HW_REG_HW_ID, 0, 6)
	s_and_b32 s3, s3, 63
	s_lshl_b32 s3, s3, 2
	s_add_i32 s3, s3, 0
	s_add_i32 s3, s3, 0x27ef0
	v_mov_b32_e32 v10, s3
	ds_read_b32 v10, v10
	s_waitcnt lgkmcnt(0)
	v_readfirstlane_b32 s3, v10
	s_nop 1
	v_lshl_add_u32 v98, s3, 6, v213
	s_nop 0
	v_cmp_eq_u32_e64 s[36:37], 0, v98
	s_and_saveexec_b64 s[4:5], s[36:37]
	s_cbranch_execz .LBB0_303
	s_mov_b64 s[8:9], exec
	v_mbcnt_lo_u32_b32 v10, s8, 0
	v_mbcnt_hi_u32_b32 v10, s9, v10
	v_cmp_eq_u32_e32 vcc, 0, v10
	s_and_saveexec_b64 s[6:7], vcc
	s_cbranch_execz .LBB0_302
	s_bcnt1_i32_b64 s3, s[8:9]
	v_mov_b32_e32 v11, s3
	global_atomic_add v106, v[0:1], v11, off sc0

; __global__ void __launch_bounds__(512, 2) fwd_megakernel(Ptrs Parg) {
;     ...
;               if (t2 == 0) misc[2] = nxt;
;               __syncthreads();
;               it = (int)__builtin_amdgcn_readfirstlane(misc[2]); } }
.LBB0_612:
	v_readlane_b32 s3, v255, 22
	s_nop 1
	v_mov_b32_e32 v10, s3
	s_waitcnt vmcnt(0)
	ds_write_b32 v10, v106
	s_branch .LBB0_298
